# P2 sample conv-state outputs: a thread's three elements are loaded together and stored after one wait (was three dependent cold round trips at the end of the phase)
# speedup vs baseline: 1.0694x; 1.0063x over previous
.LBB0_628:
	s_or_b64 exec, exec, s[6:7]
	s_mov_b32 s0, 0x60000
	v_cmp_gt_i32_e32 vcc, s0, v0
	s_and_saveexec_b64 s[0:1], vcc
	s_cbranch_execz .LBB0_635
	v_ashrrev_i32_e32 v1, 31, v0
	s_waitcnt lgkmcnt(0)
	v_lshl_add_u64 v[2:3], v[0:1], 2, s[26:27]
	s_mov_b64 s[6:7], 0x549c080
	s_ashr_i32 s3, s2, 31
	v_lshl_add_u64 v[2:3], v[2:3], 0, s[6:7]
	s_lshl_b64 s[6:7], s[2:3], 2
	s_mov_b64 s[8:9], 0
	s_mov_b32 s3, 0x2aaaaaab
	s_mov_b32 s12, 0x55555556
	v_mov_b32_e32 v5, 0
	s_mov_b32 s13, 0x5ffff
	s_cmp_lg_u32 s2, 0x20000
	s_cbranch_scc1 .LBB0_631
	v_mul_hi_i32 v1, v0, s3
	v_lshrrev_b32_e32 v4, 31, v1
	v_ashrrev_i32_e32 v1, 9, v1
	v_add_u32_e32 v6, v1, v4
	v_ashrrev_i32_e32 v1, 31, v0
	v_lshrrev_b32_e32 v1, 22, v1
	v_add_u32_e32 v1, v0, v1
	v_ashrrev_i32_e32 v1, 10, v1
	v_mul_hi_i32 v4, v1, s12
	v_lshrrev_b32_e32 v7, 31, v4
	v_add_u32_e32 v4, v4, v7
	v_lshl_add_u32 v4, v4, 1, v4
	v_sub_u32_e32 v7, v1, v4
	v_and_b32_e32 v1, 0x3ff, v0
	v_cmp_lt_i32_e32 vcc, 1, v7
	s_and_saveexec_b64 s[10:11], vcc
	s_mov_b64 s[8:9], exec
	s_cbranch_execz .Lconv2_k0_b
	v_ashrrev_i32_e32 v7, 31, v6
	v_lshlrev_b64 v[6:7], 13, v[6:7]
	v_lshl_add_u64 v[6:7], s[4:5], 0, v[6:7]
	v_lshlrev_b32_e32 v4, 1, v1
	v_lshl_add_u64 v[6:7], v[6:7], 0, v[4:5]
	v_add_co_u32_e32 v6, vcc, 0x8000000, v6
	s_nop 1
	v_addc_co_u32_e32 v7, vcc, 0, v7, vcc
	global_load_ushort v16, v[6:7], off
.Lconv2_k0_b:
	s_andn2_b64 exec, s[10:11], s[8:9]
	s_cbranch_execz .Lconv2_k0_e
	v_readlane_b32 s44, v255, 9
	v_readlane_b32 s45, v255, 10
	v_lshlrev_b32_e32 v8, 10, v7
	v_mul_hi_i32_i24_e32 v7, 0x3000, v6
	v_mul_i32_i24_e32 v6, 0x3000, v6
	v_ashrrev_i32_e32 v9, 31, v8
	v_lshlrev_b32_e32 v4, 2, v1
	v_lshl_add_u64 v[6:7], s[44:45], 0, v[6:7]
	v_lshl_add_u64 v[6:7], v[8:9], 2, v[6:7]
	v_lshl_add_u64 v[6:7], v[6:7], 0, v[4:5]
	v_add_co_u32_e32 v6, vcc, 0x1000, v6
	s_nop 0
	v_addc_co_u32_e32 v7, vcc, 0, v7, vcc
	global_load_dword v16, v[6:7], off
.Lconv2_k0_e:
	s_mov_b64 exec, s[10:11]
	v_add_u32_e32 v0, s2, v0
	v_mul_hi_i32 v1, v0, s3
	v_lshrrev_b32_e32 v4, 31, v1
	v_ashrrev_i32_e32 v1, 9, v1
	v_add_u32_e32 v6, v1, v4
	v_ashrrev_i32_e32 v1, 31, v0
	v_lshrrev_b32_e32 v1, 22, v1
	v_add_u32_e32 v1, v0, v1
	v_ashrrev_i32_e32 v1, 10, v1
	v_mul_hi_i32 v4, v1, s12
	v_lshrrev_b32_e32 v7, 31, v4
	v_add_u32_e32 v4, v4, v7
	v_lshl_add_u32 v4, v4, 1, v4
	v_sub_u32_e32 v7, v1, v4
	v_and_b32_e32 v1, 0x3ff, v0
	v_cmp_lt_i32_e32 vcc, 1, v7
	s_and_saveexec_b64 s[10:11], vcc
	s_mov_b64 s[98:99], exec
	s_cbranch_execz .Lconv2_k1_b
	v_ashrrev_i32_e32 v7, 31, v6
	v_lshlrev_b64 v[6:7], 13, v[6:7]
	v_lshl_add_u64 v[6:7], s[4:5], 0, v[6:7]
	v_lshlrev_b32_e32 v4, 1, v1
	v_lshl_add_u64 v[6:7], v[6:7], 0, v[4:5]
	v_add_co_u32_e32 v6, vcc, 0x8000000, v6
	s_nop 1
	v_addc_co_u32_e32 v7, vcc, 0, v7, vcc
	global_load_ushort v17, v[6:7], off
.Lconv2_k1_b:
	s_andn2_b64 exec, s[10:11], s[98:99]
	s_cbranch_execz .Lconv2_k1_e
	v_readlane_b32 s44, v255, 9
	v_readlane_b32 s45, v255, 10
	v_lshlrev_b32_e32 v8, 10, v7
	v_mul_hi_i32_i24_e32 v7, 0x3000, v6
	v_mul_i32_i24_e32 v6, 0x3000, v6
	v_ashrrev_i32_e32 v9, 31, v8
	v_lshlrev_b32_e32 v4, 2, v1
	v_lshl_add_u64 v[6:7], s[44:45], 0, v[6:7]
	v_lshl_add_u64 v[6:7], v[8:9], 2, v[6:7]
	v_lshl_add_u64 v[6:7], v[6:7], 0, v[4:5]
	v_add_co_u32_e32 v6, vcc, 0x1000, v6
	s_nop 0
	v_addc_co_u32_e32 v7, vcc, 0, v7, vcc
	global_load_dword v17, v[6:7], off
.Lconv2_k1_e:
	s_mov_b64 exec, s[10:11]
	v_add_u32_e32 v0, s2, v0
	v_mul_hi_i32 v1, v0, s3
	v_lshrrev_b32_e32 v4, 31, v1
	v_ashrrev_i32_e32 v1, 9, v1
	v_add_u32_e32 v6, v1, v4
	v_ashrrev_i32_e32 v1, 31, v0
	v_lshrrev_b32_e32 v1, 22, v1
	v_add_u32_e32 v1, v0, v1
	v_ashrrev_i32_e32 v1, 10, v1
	v_mul_hi_i32 v4, v1, s12
	v_lshrrev_b32_e32 v7, 31, v4
	v_add_u32_e32 v4, v4, v7
	v_lshl_add_u32 v4, v4, 1, v4
	v_sub_u32_e32 v7, v1, v4
	v_and_b32_e32 v1, 0x3ff, v0
	v_cmp_lt_i32_e32 vcc, 1, v7
	s_and_saveexec_b64 s[10:11], vcc
	s_mov_b64 s[100:101], exec
	s_cbranch_execz .Lconv2_k2_b
	v_ashrrev_i32_e32 v7, 31, v6
	v_lshlrev_b64 v[6:7], 13, v[6:7]
	v_lshl_add_u64 v[6:7], s[4:5], 0, v[6:7]
	v_lshlrev_b32_e32 v4, 1, v1
	v_lshl_add_u64 v[6:7], v[6:7], 0, v[4:5]
	v_add_co_u32_e32 v6, vcc, 0x8000000, v6
	s_nop 1
	v_addc_co_u32_e32 v7, vcc, 0, v7, vcc
	global_load_ushort v18, v[6:7], off
.Lconv2_k2_b:
	s_andn2_b64 exec, s[10:11], s[100:101]
	s_cbranch_execz .Lconv2_k2_e
	v_readlane_b32 s44, v255, 9
	v_readlane_b32 s45, v255, 10
	v_lshlrev_b32_e32 v8, 10, v7
	v_mul_hi_i32_i24_e32 v7, 0x3000, v6
	v_mul_i32_i24_e32 v6, 0x3000, v6
	v_ashrrev_i32_e32 v9, 31, v8
	v_lshlrev_b32_e32 v4, 2, v1
	v_lshl_add_u64 v[6:7], s[44:45], 0, v[6:7]
	v_lshl_add_u64 v[6:7], v[8:9], 2, v[6:7]
	v_lshl_add_u64 v[6:7], v[6:7], 0, v[4:5]
	v_add_co_u32_e32 v6, vcc, 0x1000, v6
	s_nop 0
	v_addc_co_u32_e32 v7, vcc, 0, v7, vcc
	global_load_dword v18, v[6:7], off
.Lconv2_k2_e:
	s_mov_b64 exec, s[10:11]
	v_add_u32_e32 v0, s2, v0
	s_waitcnt vmcnt(0)
	s_mov_b64 s[10:11], exec
	s_mov_b64 exec, s[8:9]
	v_lshlrev_b32_e32 v16, 16, v16
	s_mov_b64 exec, s[98:99]
	v_lshlrev_b32_e32 v17, 16, v17
	s_mov_b64 exec, s[100:101]
	v_lshlrev_b32_e32 v18, 16, v18
	s_mov_b64 exec, s[10:11]
	global_store_dword v[2:3], v16, off
	v_lshl_add_u64 v[2:3], v[2:3], 0, s[6:7]
	global_store_dword v[2:3], v17, off
	v_lshl_add_u64 v[2:3], v[2:3], 0, s[6:7]
	global_store_dword v[2:3], v18, off
	s_branch .LBB0_635
	s_branch .LBB0_631
